# in_proj epilogue: short straight-line path for plain bf16 column tiles (one base address + 7 row offsets, 16 stores); gate and dt tiles keep the original code
# baseline (speedup 1.0000x reference)
; template <class Epi>
; __device__ __forceinline__ void gemm_phase(LAS unsigned char* lds, const GemmD g, const Epi& E) {
;     ...
;         for (int t = 0; t < nt; t += 2) PG8_KITER(t);
.LBB0_181:
	ds_read_b128 v[144:147], v157
	ds_read_b128 v[148:151], v157 offset:1024
	ds_read_b128 v[162:165], v157 offset:2048
	ds_read_b128 v[166:169], v157 offset:3072
	s_add_u32 s30, s28, 0xfff80080
	s_addc_u32 s31, s29, -1
	s_cmp_eq_u32 s54, 28
	s_cselect_b32 s35, s2, s31
	s_cselect_b32 s34, s3, s30
	s_cselect_b32 s31, s7, s27
	s_cselect_b32 s30, s9, s11
	v_lshl_add_u64 v[152:153], s[28:29], 0, v[136:137]
	s_add_i32 m0, s39, 0xc000
	ds_read_b128 v[170:173], v158
	ds_read_b128 v[174:177], v158 offset:1024
	ds_read_b128 v[178:181], v158 offset:2048
	ds_read_b128 v[186:189], v158 offset:3072
	ds_read_b128 v[194:197], v158 offset:4096
	ds_read_b128 v[198:201], v158 offset:5120
	ds_read_b128 v[202:205], v158 offset:6144
	ds_read_b128 v[206:209], v158 offset:7168
	global_load_lds_dwordx4 v[152:153], off
	v_lshl_add_u64 v[152:153], s[28:29], 0, v[138:139]
	s_add_i32 m0, s39, 0xe000
	s_nop 0
	global_load_lds_dwordx4 v[152:153], off
	ds_read_b128 v[210:213], v159
	ds_read_b128 v[214:217], v159 offset:1024
	ds_read_b128 v[218:221], v159 offset:2048
	ds_read_b128 v[222:225], v159 offset:3072
	s_waitcnt lgkmcnt(0)
	s_barrier
	s_setprio 1
	v_mfma_f32_16x16x32_bf16 v[124:127], v[144:147], v[170:173], v[124:127]
	v_mfma_f32_16x16x32_bf16 v[120:123], v[162:165], v[170:173], v[120:123]
	v_mfma_f32_16x16x32_bf16 v[108:111], v[144:147], v[178:181], v[108:111]
	v_mfma_f32_16x16x32_bf16 v[104:107], v[162:165], v[178:181], v[104:107]
	v_mfma_f32_16x16x32_bf16 v[92:95], v[144:147], v[194:197], v[92:95]
	v_mfma_f32_16x16x32_bf16 v[88:91], v[162:165], v[194:197], v[88:91]
	v_mfma_f32_16x16x32_bf16 v[76:79], v[144:147], v[202:205], v[76:79]
	v_mfma_f32_16x16x32_bf16 v[72:75], v[162:165], v[202:205], v[72:75]
	v_mfma_f32_16x16x32_bf16 v[124:127], v[148:151], v[174:177], v[124:127]
	v_mfma_f32_16x16x32_bf16 v[120:123], v[166:169], v[174:177], v[120:123]
	v_mfma_f32_16x16x32_bf16 v[108:111], v[148:151], v[186:189], v[108:111]
	v_mfma_f32_16x16x32_bf16 v[104:107], v[166:169], v[186:189], v[104:107]
	v_mfma_f32_16x16x32_bf16 v[92:95], v[148:151], v[198:201], v[92:95]
	v_mfma_f32_16x16x32_bf16 v[88:91], v[166:169], v[198:201], v[88:91]
	v_mfma_f32_16x16x32_bf16 v[76:79], v[148:151], v[206:209], v[76:79]
	v_mfma_f32_16x16x32_bf16 v[72:75], v[166:169], v[206:209], v[72:75]
	v_mfma_f32_16x16x32_bf16 v[116:119], v[210:213], v[170:173], v[116:119]
	v_mfma_f32_16x16x32_bf16 v[112:115], v[218:221], v[170:173], v[112:115]
	v_mfma_f32_16x16x32_bf16 v[100:103], v[210:213], v[178:181], v[100:103]
	v_mfma_f32_16x16x32_bf16 v[96:99], v[218:221], v[178:181], v[96:99]
	v_mfma_f32_16x16x32_bf16 v[84:87], v[210:213], v[194:197], v[84:87]
	v_mfma_f32_16x16x32_bf16 v[80:83], v[218:221], v[194:197], v[80:83]
	v_mfma_f32_16x16x32_bf16 v[68:71], v[210:213], v[202:205], v[68:71]
	v_mfma_f32_16x16x32_bf16 v[64:67], v[218:221], v[202:205], v[64:67]
	v_mfma_f32_16x16x32_bf16 v[116:119], v[214:217], v[174:177], v[116:119]
	v_mfma_f32_16x16x32_bf16 v[112:115], v[222:225], v[174:177], v[112:115]
	v_mfma_f32_16x16x32_bf16 v[100:103], v[214:217], v[186:189], v[100:103]
	v_mfma_f32_16x16x32_bf16 v[96:99], v[222:225], v[186:189], v[96:99]
	v_mfma_f32_16x16x32_bf16 v[84:87], v[214:217], v[198:201], v[84:87]
	v_mfma_f32_16x16x32_bf16 v[80:83], v[222:225], v[198:201], v[80:83]
	v_mfma_f32_16x16x32_bf16 v[68:71], v[214:217], v[206:209], v[68:71]
	v_mfma_f32_16x16x32_bf16 v[64:67], v[222:225], v[206:209], v[64:67]
	s_setprio 0
	s_barrier
	s_add_i32 s55, s48, s38
	v_lshl_add_u64 v[152:153], s[30:31], 0, v[130:131]
	s_mov_b32 m0, s55
	s_nop 0
	global_load_lds_dwordx4 v[152:153], off
	v_lshl_add_u64 v[182:183], s[30:31], 0, v[134:135]
	s_add_i32 m0, s55, 0x2000
	s_nop 0
	global_load_lds_dwordx4 v[182:183], off
	s_mov_b32 m0, s39
	v_lshl_add_u64 v[190:191], s[34:35], 0, v[128:129]
	ds_read_b128 v[170:173], v158 offset:16384
	ds_read_b128 v[174:177], v158 offset:17408
	ds_read_b128 v[178:181], v158 offset:18432
	ds_read_b128 v[186:189], v158 offset:19456
	ds_read_b128 v[194:197], v158 offset:20480
	ds_read_b128 v[198:201], v158 offset:21504
	ds_read_b128 v[202:205], v158 offset:22528
	ds_read_b128 v[206:209], v158 offset:23552
	global_load_lds_dwordx4 v[190:191], off
	v_lshl_add_u64 v[226:227], s[34:35], 0, v[132:133]
	s_mov_b32 m0, s40
	s_nop 0
	global_load_lds_dwordx4 v[226:227], off
	s_add_u32 s56, s30, 0x80000
	s_addc_u32 s57, s31, 0
	s_add_i32 s55, s49, s38
	v_lshl_add_u64 v[246:247], s[56:57], 0, v[130:131]
	s_mov_b32 m0, s55
	s_nop 0
	global_load_lds_dwordx4 v[246:247], off
	v_lshl_add_u64 v[248:249], s[56:57], 0, v[134:135]
	s_add_i32 m0, s55, 0x2000
	s_nop 0
	global_load_lds_dwordx4 v[248:249], off
	s_add_i32 s55, 0, 0x18000
	v_add_u32_e32 v161, s55, v155
	s_waitcnt vmcnt(6)
	s_waitcnt lgkmcnt(0)
	s_barrier
; template <class Epi>
; __device__ __forceinline__ void gemm_phase(LAS unsigned char* lds, const GemmD g, const Epi& E) {
;     ...
;         for (int t = 0; t < nt; t += 2) PG8_KITER(t);
	s_setprio 1
	v_mfma_f32_16x16x32_bf16 v[60:63], v[144:147], v[170:173], v[60:63]
	v_mfma_f32_16x16x32_bf16 v[56:59], v[162:165], v[170:173], v[56:59]
	v_mfma_f32_16x16x32_bf16 v[44:47], v[144:147], v[178:181], v[44:47]
	v_mfma_f32_16x16x32_bf16 v[40:43], v[162:165], v[178:181], v[40:43]
	v_mfma_f32_16x16x32_bf16 v[28:31], v[144:147], v[194:197], v[28:31]
	v_mfma_f32_16x16x32_bf16 v[24:27], v[162:165], v[194:197], v[24:27]
	v_mfma_f32_16x16x32_bf16 v[12:15], v[144:147], v[202:205], v[12:15]
	v_mfma_f32_16x16x32_bf16 v[8:11], v[162:165], v[202:205], v[8:11]
	v_mfma_f32_16x16x32_bf16 v[60:63], v[148:151], v[174:177], v[60:63]
	v_mfma_f32_16x16x32_bf16 v[56:59], v[166:169], v[174:177], v[56:59]
	v_mfma_f32_16x16x32_bf16 v[44:47], v[148:151], v[186:189], v[44:47]
	v_mfma_f32_16x16x32_bf16 v[40:43], v[166:169], v[186:189], v[40:43]
	v_mfma_f32_16x16x32_bf16 v[28:31], v[148:151], v[198:201], v[28:31]
	v_mfma_f32_16x16x32_bf16 v[24:27], v[166:169], v[198:201], v[24:27]
	v_mfma_f32_16x16x32_bf16 v[12:15], v[148:151], v[206:209], v[12:15]
	v_mfma_f32_16x16x32_bf16 v[8:11], v[166:169], v[206:209], v[8:11]
	v_mfma_f32_16x16x32_bf16 v[52:55], v[210:213], v[170:173], v[52:55]
	v_mfma_f32_16x16x32_bf16 v[48:51], v[218:221], v[170:173], v[48:51]
	v_mfma_f32_16x16x32_bf16 v[36:39], v[210:213], v[178:181], v[36:39]
	v_mfma_f32_16x16x32_bf16 v[32:35], v[218:221], v[178:181], v[32:35]
	v_mfma_f32_16x16x32_bf16 v[20:23], v[210:213], v[194:197], v[20:23]
	v_mfma_f32_16x16x32_bf16 v[16:19], v[218:221], v[194:197], v[16:19]
	v_mfma_f32_16x16x32_bf16 v[4:7], v[210:213], v[202:205], v[4:7]
	v_mfma_f32_16x16x32_bf16 v[0:3], v[218:221], v[202:205], v[0:3]
	v_mfma_f32_16x16x32_bf16 v[52:55], v[214:217], v[174:177], v[52:55]
	v_mfma_f32_16x16x32_bf16 v[48:51], v[222:225], v[174:177], v[48:51]
	v_mfma_f32_16x16x32_bf16 v[36:39], v[214:217], v[186:189], v[36:39]
	v_mfma_f32_16x16x32_bf16 v[32:35], v[222:225], v[186:189], v[32:35]
	v_mfma_f32_16x16x32_bf16 v[20:23], v[214:217], v[198:201], v[20:23]
	v_mfma_f32_16x16x32_bf16 v[16:19], v[222:225], v[198:201], v[16:19]
	v_mfma_f32_16x16x32_bf16 v[4:7], v[214:217], v[206:209], v[4:7]
	v_mfma_f32_16x16x32_bf16 v[0:3], v[222:225], v[206:209], v[0:3]
	s_setprio 0
	s_barrier
	ds_read_b128 v[144:147], v161
	ds_read_b128 v[148:151], v161 offset:1024
	ds_read_b128 v[162:165], v161 offset:2048
	ds_read_b128 v[166:169], v161 offset:3072
	s_add_u32 s34, s34, 0x80000
	s_addc_u32 s35, s35, 0
	s_mov_b32 m0, s41
	v_lshl_add_u64 v[250:251], s[34:35], 0, v[128:129]
	ds_read_b128 v[170:173], v158 offset:32768
	ds_read_b128 v[174:177], v158 offset:33792
	ds_read_b128 v[178:181], v158 offset:34816
	ds_read_b128 v[186:189], v158 offset:35840
	ds_read_b128 v[194:197], v158 offset:36864
	ds_read_b128 v[198:201], v158 offset:37888
	ds_read_b128 v[202:205], v158 offset:38912
	ds_read_b128 v[206:209], v158 offset:39936
	global_load_lds_dwordx4 v[250:251], off
	v_lshl_add_u64 v[252:253], s[34:35], 0, v[132:133]
	s_mov_b32 m0, s42
	s_nop 0
	global_load_lds_dwordx4 v[252:253], off
	v_add_u32_e32 v161, 0x1c000, v155
	ds_read_b128 v[210:213], v161
	ds_read_b128 v[214:217], v161 offset:1024
	ds_read_b128 v[218:221], v161 offset:2048
	ds_read_b128 v[222:225], v161 offset:3072
	s_waitcnt lgkmcnt(0)
	s_barrier
	s_setprio 1
	v_mfma_f32_16x16x32_bf16 v[124:127], v[144:147], v[170:173], v[124:127]
	v_mfma_f32_16x16x32_bf16 v[120:123], v[162:165], v[170:173], v[120:123]
	v_mfma_f32_16x16x32_bf16 v[108:111], v[144:147], v[178:181], v[108:111]
	v_mfma_f32_16x16x32_bf16 v[104:107], v[162:165], v[178:181], v[104:107]
	v_mfma_f32_16x16x32_bf16 v[92:95], v[144:147], v[194:197], v[92:95]
	v_mfma_f32_16x16x32_bf16 v[88:91], v[162:165], v[194:197], v[88:91]
	v_mfma_f32_16x16x32_bf16 v[76:79], v[144:147], v[202:205], v[76:79]
	v_mfma_f32_16x16x32_bf16 v[72:75], v[162:165], v[202:205], v[72:75]
	v_mfma_f32_16x16x32_bf16 v[124:127], v[148:151], v[174:177], v[124:127]
	v_mfma_f32_16x16x32_bf16 v[120:123], v[166:169], v[174:177], v[120:123]
	v_mfma_f32_16x16x32_bf16 v[108:111], v[148:151], v[186:189], v[108:111]
	v_mfma_f32_16x16x32_bf16 v[104:107], v[166:169], v[186:189], v[104:107]
	v_mfma_f32_16x16x32_bf16 v[92:95], v[148:151], v[198:201], v[92:95]
	v_mfma_f32_16x16x32_bf16 v[88:91], v[166:169], v[198:201], v[88:91]
	v_mfma_f32_16x16x32_bf16 v[76:79], v[148:151], v[206:209], v[76:79]
	v_mfma_f32_16x16x32_bf16 v[72:75], v[166:169], v[206:209], v[72:75]
	v_mfma_f32_16x16x32_bf16 v[116:119], v[210:213], v[170:173], v[116:119]
	v_mfma_f32_16x16x32_bf16 v[112:115], v[218:221], v[170:173], v[112:115]
	v_mfma_f32_16x16x32_bf16 v[100:103], v[210:213], v[178:181], v[100:103]
	v_mfma_f32_16x16x32_bf16 v[96:99], v[218:221], v[178:181], v[96:99]
	v_mfma_f32_16x16x32_bf16 v[84:87], v[210:213], v[194:197], v[84:87]
	v_mfma_f32_16x16x32_bf16 v[80:83], v[218:221], v[194:197], v[80:83]
	v_mfma_f32_16x16x32_bf16 v[68:71], v[210:213], v[202:205], v[68:71]
	v_mfma_f32_16x16x32_bf16 v[64:67], v[218:221], v[202:205], v[64:67]
	v_mfma_f32_16x16x32_bf16 v[116:119], v[214:217], v[174:177], v[116:119]
	v_mfma_f32_16x16x32_bf16 v[112:115], v[222:225], v[174:177], v[112:115]
	v_mfma_f32_16x16x32_bf16 v[100:103], v[214:217], v[186:189], v[100:103]
	v_mfma_f32_16x16x32_bf16 v[96:99], v[222:225], v[186:189], v[96:99]
	v_mfma_f32_16x16x32_bf16 v[84:87], v[214:217], v[198:201], v[84:87]
	v_mfma_f32_16x16x32_bf16 v[80:83], v[222:225], v[198:201], v[80:83]
	v_mfma_f32_16x16x32_bf16 v[68:71], v[214:217], v[206:209], v[68:71]
	v_mfma_f32_16x16x32_bf16 v[64:67], v[222:225], v[206:209], v[64:67]
	s_setprio 0
	s_barrier
; template <class Epi>
; __device__ __forceinline__ void gemm_phase(LAS unsigned char* lds, const GemmD g, const Epi& E) {
;     ...
;         for (int t = 0; t < nt; t += 2) PG8_KITER(t);
;     __device__ __forceinline__ void operator()(const f32x4 (&acc)[2][2][4][2], const Unit& u, int wr, int wc, int fr, int fq) const {
;         const int row0 = u.pm * BM + wr * 64 + fr, col0 = u.pn * BM + wc * 32 + 8 * fq;
;         const bool sig = (u.pn >= 36 && u.pn < 52), isdt = (u.pn == 52);
; #pragma unroll
;         for (int ai = 0; ai < 2; ++ai)
; #pragma unroll
;             for (int m = 0; m < 4; ++m) { const int row = row0 + ai * HALF + m * 16;
; #pragma unroll
;                 for (int bj = 0; bj < 2; ++bj) { const f32x4 v0 = acc[ai][bj][m][0], v1 = acc[ai][bj][m][1]; const int col = col0 + bj * HALF;
;                     if (sig) {
;                         const int c = (col - C_GS) >> 1;
	s_add_i32 s34, 0, 0x1c000
	s_add_i32 s35, s55, s38
	v_lshl_add_u64 v[152:153], v[152:153], 0, s[0:1]
	s_mov_b32 m0, s35
	s_nop 0
	global_load_lds_dwordx4 v[152:153], off
	v_lshl_add_u64 v[152:153], v[182:183], 0, s[0:1]
	s_add_i32 m0, s35, 0x2000
	s_nop 0
	global_load_lds_dwordx4 v[152:153], off
	s_mov_b32 m0, s44
	v_lshl_add_u64 v[152:153], v[190:191], 0, s[0:1]
	ds_read_b128 v[170:173], v158 offset:49152
	ds_read_b128 v[174:177], v158 offset:50176
	ds_read_b128 v[178:181], v158 offset:51200
	ds_read_b128 v[186:189], v158 offset:52224
	ds_read_b128 v[194:197], v158 offset:53248
	ds_read_b128 v[198:201], v158 offset:54272
	ds_read_b128 v[202:205], v158 offset:55296
	ds_read_b128 v[206:209], v158 offset:56320
	global_load_lds_dwordx4 v[152:153], off
	v_lshl_add_u64 v[152:153], v[226:227], 0, s[0:1]
	s_mov_b32 m0, s45
	s_nop 0
	global_load_lds_dwordx4 v[152:153], off
	s_add_u32 s30, s30, 0x80080
	s_addc_u32 s31, s31, 0
	s_add_i32 s34, s34, s38
	v_lshl_add_u64 v[246:247], s[30:31], 0, v[130:131]
	s_mov_b32 m0, s34
	s_nop 0
	global_load_lds_dwordx4 v[246:247], off
	v_lshl_add_u64 v[248:249], s[30:31], 0, v[134:135]
	s_add_i32 m0, s34, 0x2000
	s_nop 0
	global_load_lds_dwordx4 v[248:249], off
	s_add_i32 s54, s54, 2
	s_add_u32 s28, s28, 0x100
	s_addc_u32 s29, s29, 0
	s_add_u32 s11, s11, 0x100
	s_addc_u32 s27, s27, 0
	s_cmp_gt_u32 s54, 29
	s_waitcnt vmcnt(6)
	s_waitcnt lgkmcnt(0)
	s_barrier
	s_setprio 1
	v_mfma_f32_16x16x32_bf16 v[60:63], v[144:147], v[170:173], v[60:63]
	v_mfma_f32_16x16x32_bf16 v[56:59], v[162:165], v[170:173], v[56:59]
	v_mfma_f32_16x16x32_bf16 v[44:47], v[144:147], v[178:181], v[44:47]
	v_mfma_f32_16x16x32_bf16 v[40:43], v[162:165], v[178:181], v[40:43]
	v_mfma_f32_16x16x32_bf16 v[28:31], v[144:147], v[194:197], v[28:31]
	v_mfma_f32_16x16x32_bf16 v[24:27], v[162:165], v[194:197], v[24:27]
	v_mfma_f32_16x16x32_bf16 v[12:15], v[144:147], v[202:205], v[12:15]
	v_mfma_f32_16x16x32_bf16 v[8:11], v[162:165], v[202:205], v[8:11]
	v_mfma_f32_16x16x32_bf16 v[60:63], v[148:151], v[174:177], v[60:63]
	v_mfma_f32_16x16x32_bf16 v[56:59], v[166:169], v[174:177], v[56:59]
	v_mfma_f32_16x16x32_bf16 v[44:47], v[148:151], v[186:189], v[44:47]
	v_mfma_f32_16x16x32_bf16 v[40:43], v[166:169], v[186:189], v[40:43]
	v_mfma_f32_16x16x32_bf16 v[28:31], v[148:151], v[198:201], v[28:31]
	v_mfma_f32_16x16x32_bf16 v[24:27], v[166:169], v[198:201], v[24:27]
	v_mfma_f32_16x16x32_bf16 v[12:15], v[148:151], v[206:209], v[12:15]
	v_mfma_f32_16x16x32_bf16 v[8:11], v[166:169], v[206:209], v[8:11]
	v_mfma_f32_16x16x32_bf16 v[52:55], v[210:213], v[170:173], v[52:55]
	v_mfma_f32_16x16x32_bf16 v[48:51], v[218:221], v[170:173], v[48:51]
	v_mfma_f32_16x16x32_bf16 v[36:39], v[210:213], v[178:181], v[36:39]
	v_mfma_f32_16x16x32_bf16 v[32:35], v[218:221], v[178:181], v[32:35]
	v_mfma_f32_16x16x32_bf16 v[20:23], v[210:213], v[194:197], v[20:23]
	v_mfma_f32_16x16x32_bf16 v[16:19], v[218:221], v[194:197], v[16:19]
	v_mfma_f32_16x16x32_bf16 v[4:7], v[210:213], v[202:205], v[4:7]
	v_mfma_f32_16x16x32_bf16 v[0:3], v[218:221], v[202:205], v[0:3]
	v_mfma_f32_16x16x32_bf16 v[52:55], v[214:217], v[174:177], v[52:55]
	v_mfma_f32_16x16x32_bf16 v[48:51], v[222:225], v[174:177], v[48:51]
	v_mfma_f32_16x16x32_bf16 v[36:39], v[214:217], v[186:189], v[36:39]
	v_mfma_f32_16x16x32_bf16 v[32:35], v[222:225], v[186:189], v[32:35]
	v_mfma_f32_16x16x32_bf16 v[20:23], v[214:217], v[198:201], v[20:23]
	v_mfma_f32_16x16x32_bf16 v[16:19], v[222:225], v[198:201], v[16:19]
	v_mfma_f32_16x16x32_bf16 v[4:7], v[214:217], v[206:209], v[4:7]
	v_mfma_f32_16x16x32_bf16 v[0:3], v[222:225], v[206:209], v[0:3]
	s_setprio 0
	s_barrier
	s_cbranch_scc0 .LBB0_181
	s_sub_i32 s2, s6, 36
	v_lshl_add_u32 v146, s26, 8, v154
	s_cmp_gt_u32 s2, 15
	s_cselect_b64 s[28:29], -1, 0
	s_cmp_eq_u32 s6, 52
	v_ashrrev_i32_e32 v147, 31, v146
	v_mad_i64_i32 v[152:153], s[2:3], v146, s50, 0
	v_lshl_or_b32 v144, s6, 8, v156
	s_cselect_b64 s[26:27], -1, 0
	v_lshlrev_b64 v[150:151], 7, v[146:147]
	s_mov_b64 s[2:3], -1
	s_and_b64 vcc, exec, s[28:29]
	s_cbranch_vccz .LBB0_186
	s_and_b64 vcc, exec, s[26:27]
	s_cbranch_vccnz .Lproj_slow
; __device__ __forceinline__ unsigned pk2(float lo, float hi) { unsigned r; asm("v_cvt_pk_bf16_f32 %0, %1, %2" : "=v"(r) : "v"(lo), "v"(hi)); return r; }
;     __device__ __forceinline__ void operator()(const f32x4 (&acc)[2][2][4][2], const Unit& u, int wr, int wc, int fr, int fq) const {
;         const int row0 = u.pm * BM + wr * 64 + fr, col0 = u.pn * BM + wc * 32 + 8 * fq;
;         const bool sig = (u.pn >= 36 && u.pn < 52), isdt = (u.pn == 52);
; #pragma unroll
;         for (int ai = 0; ai < 2; ++ai)
; #pragma unroll
;             for (int m = 0; m < 4; ++m) { const int row = row0 + ai * HALF + m * 16;
; #pragma unroll
;                 for (int bj = 0; bj < 2; ++bj) { const f32x4 v0 = acc[ai][bj][m][0], v1 = acc[ai][bj][m][1]; const int col = col0 + bj * HALF;
;                     if (sig) {
;                         const int c = (col - C_GS) >> 1;
;                         float ra[4], gp[4];
; #pragma unroll
;                         for (int j = 0; j < 4; ++j) { const float ea = __expf(-fminf(fmaxf(v0[j], -30.f), 30.f)), eb = __expf(-fminf(fmaxf(v1[j], -30.f), 30.f)); gp[j] = __builtin_amdgcn_rcpf(1.0f + eb); ra[j] = (1.0f + eb) * __builtin_amdgcn_rcpf(1.0f + ea); }
;                         u32x2 wr_, wg; wr_.x = pk2(ra[0], ra[1]); wr_.y = pk2(ra[2], ra[3]); wg.x = pk2(gp[0], gp[1]); wg.y = pk2(gp[2], gp[3]);
;                         *(u32x2*)(proj + (size_t)row * NPROJ + C_GS + c) = wr_;
;                         *(u32x2*)(proj + (size_t)row * NPROJ + C_GP + c) = wg;
;                     } else {
;                         u32x4 w; w.x = pk2(v0[0], v0[1]); w.y = pk2(v0[2], v0[3]); w.z = pk2(v1[0], v1[1]); w.w = pk2(v1[2], v1[3]);
;                         *(u32x4*)(proj + (size_t)row * NPROJ + col) = w;
;                         if (isdt && col < C_DT + 32) { float* d = dtraw + (size_t)row * 32 + (col - C_DT); *(f32x4*)d = v0; *(f32x4*)(d + 4) = v1; } } } }
	v_lshl_add_u64 v[148:149], s[92:93], 0, v[152:153]
	v_ashrrev_i32_e32 v145, 31, v144
	v_lshl_add_u64 v[148:149], v[144:145], 1, v[148:149]
	s_mov_b32 s61, 0
	s_mov_b32 s60, 0x6a000
	v_lshl_add_u64 v[226:227], v[148:149], 0, s[60:61]
	s_mov_b32 s60, 0xd4000
	v_lshl_add_u64 v[228:229], v[148:149], 0, s[60:61]
	s_mov_b32 s60, 0x13e000
	v_lshl_add_u64 v[230:231], v[148:149], 0, s[60:61]
	s_mov_b32 s60, 0x350000
	v_lshl_add_u64 v[232:233], v[148:149], 0, s[60:61]
	s_mov_b32 s60, 0x3ba000
	v_lshl_add_u64 v[234:235], v[148:149], 0, s[60:61]
	s_mov_b32 s60, 0x424000
	v_lshl_add_u64 v[236:237], v[148:149], 0, s[60:61]
	s_mov_b32 s60, 0x48e000
	v_lshl_add_u64 v[238:239], v[148:149], 0, s[60:61]
	v_cvt_pk_bf16_f32 v162, v124, v125
	v_cvt_pk_bf16_f32 v163, v126, v127
	v_cvt_pk_bf16_f32 v164, v120, v121
	v_cvt_pk_bf16_f32 v165, v122, v123
	global_store_dwordx4 v[148:149], v[162:165], off
	v_cvt_pk_bf16_f32 v246, v116, v117
	v_cvt_pk_bf16_f32 v247, v118, v119
	v_cvt_pk_bf16_f32 v248, v112, v113
	v_cvt_pk_bf16_f32 v249, v114, v115
	global_store_dwordx4 v[148:149], v[246:249], off offset:256
	v_cvt_pk_bf16_f32 v250, v108, v109
	v_cvt_pk_bf16_f32 v251, v110, v111
	v_cvt_pk_bf16_f32 v252, v104, v105
	v_cvt_pk_bf16_f32 v253, v106, v107
	global_store_dwordx4 v[226:227], v[250:253], off
	v_cvt_pk_bf16_f32 v240, v100, v101
	v_cvt_pk_bf16_f32 v241, v102, v103
	v_cvt_pk_bf16_f32 v242, v96, v97
	v_cvt_pk_bf16_f32 v243, v98, v99
	global_store_dwordx4 v[226:227], v[240:243], off offset:256
	v_cvt_pk_bf16_f32 v162, v92, v93
	v_cvt_pk_bf16_f32 v163, v94, v95
	v_cvt_pk_bf16_f32 v164, v88, v89
	v_cvt_pk_bf16_f32 v165, v90, v91
	global_store_dwordx4 v[228:229], v[162:165], off
	v_cvt_pk_bf16_f32 v246, v84, v85
	v_cvt_pk_bf16_f32 v247, v86, v87
	v_cvt_pk_bf16_f32 v248, v80, v81
	v_cvt_pk_bf16_f32 v249, v82, v83
	global_store_dwordx4 v[228:229], v[246:249], off offset:256
	v_cvt_pk_bf16_f32 v250, v76, v77
	v_cvt_pk_bf16_f32 v251, v78, v79
	v_cvt_pk_bf16_f32 v252, v72, v73
	v_cvt_pk_bf16_f32 v253, v74, v75
	global_store_dwordx4 v[230:231], v[250:253], off
	v_cvt_pk_bf16_f32 v240, v68, v69
	v_cvt_pk_bf16_f32 v241, v70, v71
	v_cvt_pk_bf16_f32 v242, v64, v65
	v_cvt_pk_bf16_f32 v243, v66, v67
	global_store_dwordx4 v[230:231], v[240:243], off offset:256
	v_cvt_pk_bf16_f32 v162, v60, v61
	v_cvt_pk_bf16_f32 v163, v62, v63
	v_cvt_pk_bf16_f32 v164, v56, v57
	v_cvt_pk_bf16_f32 v165, v58, v59
	global_store_dwordx4 v[232:233], v[162:165], off
	v_cvt_pk_bf16_f32 v246, v52, v53
	v_cvt_pk_bf16_f32 v247, v54, v55
	v_cvt_pk_bf16_f32 v248, v48, v49
	v_cvt_pk_bf16_f32 v249, v50, v51
	global_store_dwordx4 v[232:233], v[246:249], off offset:256
	v_cvt_pk_bf16_f32 v250, v44, v45
	v_cvt_pk_bf16_f32 v251, v46, v47
	v_cvt_pk_bf16_f32 v252, v40, v41
	v_cvt_pk_bf16_f32 v253, v42, v43
	global_store_dwordx4 v[234:235], v[250:253], off
	v_cvt_pk_bf16_f32 v240, v36, v37
	v_cvt_pk_bf16_f32 v241, v38, v39
	v_cvt_pk_bf16_f32 v242, v32, v33
	v_cvt_pk_bf16_f32 v243, v34, v35
	global_store_dwordx4 v[234:235], v[240:243], off offset:256
	v_cvt_pk_bf16_f32 v162, v28, v29
	v_cvt_pk_bf16_f32 v163, v30, v31
	v_cvt_pk_bf16_f32 v164, v24, v25
	v_cvt_pk_bf16_f32 v165, v26, v27
	global_store_dwordx4 v[236:237], v[162:165], off
	v_cvt_pk_bf16_f32 v246, v20, v21
	v_cvt_pk_bf16_f32 v247, v22, v23
	v_cvt_pk_bf16_f32 v248, v16, v17
	v_cvt_pk_bf16_f32 v249, v18, v19
	global_store_dwordx4 v[236:237], v[246:249], off offset:256
	v_cvt_pk_bf16_f32 v250, v12, v13
	v_cvt_pk_bf16_f32 v251, v14, v15
	v_cvt_pk_bf16_f32 v252, v8, v9
	v_cvt_pk_bf16_f32 v253, v10, v11
	global_store_dwordx4 v[238:239], v[250:253], off
	v_cvt_pk_bf16_f32 v240, v4, v5
	v_cvt_pk_bf16_f32 v241, v6, v7
	v_cvt_pk_bf16_f32 v242, v0, v1
	v_cvt_pk_bf16_f32 v243, v2, v3
	global_store_dwordx4 v[238:239], v[240:243], off offset:256
	s_branch .LBB0_173
.Lproj_slow:
	v_lshl_add_u64 v[148:149], s[92:93], 0, v[152:153]
	v_ashrrev_i32_e32 v145, 31, v144
	v_cmp_gt_i32_e32 vcc, s52, v144
	v_lshl_add_u64 v[148:149], v[144:145], 1, v[148:149]
	s_and_b64 s[2:3], s[26:27], vcc
	v_cvt_pk_bf16_f32 v162, v124, v125
	v_cvt_pk_bf16_f32 v163, v126, v127
	v_cvt_pk_bf16_f32 v164, v120, v121
	v_cvt_pk_bf16_f32 v165, v122, v123
	global_store_dwordx4 v[148:149], v[162:165], off
	s_and_saveexec_b64 s[6:7], s[2:3]
	s_cbranch_execz .LBB0_185
	v_lshl_add_u64 v[148:149], s[14:15], 0, v[150:151]
	v_lshl_add_u64 v[148:149], v[144:145], 2, v[148:149]
	v_add_co_u32_e32 v162, vcc, 0xffff3000, v148
	s_nop 1
	v_addc_co_u32_e32 v163, vcc, -1, v149, vcc
	v_add_co_u32_e32 v148, vcc, 0xffff4000, v148
	global_store_dwordx4 v[162:163], v[124:127], off
	s_nop 0
	v_addc_co_u32_e32 v149, vcc, -1, v149, vcc
	global_store_dwordx4 v[148:149], v[120:123], off offset:-4080
